# attn: indexer selection stored as f32 bias tile in LDS and fed as the QK MFMA C operand; packed sub/sum in softmax; running-max derived values kept in registers
# speedup vs baseline: 1.0058x; 1.0058x over previous
; DI void dsa_attn_item(const Params& p, int b, int qblk, char* smem) {
;   u16* maskbuf = (u16*)smem;
;   u16* qi = (u16*)(smem + 4096);
;   const u16* tm = (const u16*)(p.ws + OFF_TM);
;   const u16* vfr = (const u16*)(p.ws + OFF_VT) + ((size_t)(b * 8 + (threadIdx.x >> 6)) * 128) * 2048 + (threadIdx.x & 63) * 8;
;   const u16* kfr = (const u16*)(p.ws + OFF_KFR) + ((size_t)(b * 8 + (threadIdx.x >> 6)) * 128) * 2048 + (threadIdx.x & 63) * 8;
;   const unsigned* thr = (const unsigned*)(p.ws + OFF_THR);
;   const int tid = threadIdx.x, lane = tid & 63, wave = tid >> 6, lr = lane & 31, lh = lane >> 5;
;   const int q0 = qblk * 32;
;   const int head = wave;
;   const int qtok = b * S_ + q0 + lr;
.LBB0_423:
	s_or_b64 exec, exec, s[0:1]
	s_waitcnt lgkmcnt(0)
	v_and_b32_e32 v0, 0x1f8, v95
	v_lshlrev_b32_e32 v0, 1, v0
	v_mov_b32_e32 v1, 0
	v_lshl_add_u64 v[2:3], s[96:97], 0, v[0:1]
	s_mov_b64 s[0:1], 0x1dc00000
	v_lshl_add_u64 v[184:185], v[2:3], 0, s[0:1]
	s_mov_b64 s[0:1], 0x13c00000
	v_and_b32_e32 v4, 0x3c0, v166
	v_lshl_add_u64 v[186:187], v[2:3], 0, s[0:1]
	s_movk_i32 s0, 0x100
	v_cmp_gt_u32_e64 s[0:1], s0, v166
	v_lshlrev_b32_e32 v0, 1, v4
	v_lshl_add_u64 v[2:3], s[96:97], 0, v[0:1]
	v_writelane_b32 v255, s0, 45
	v_lshlrev_b32_e32 v0, 1, v214
	v_lshl_add_u64 v[188:189], v[2:3], 0, v[0:1]
	v_writelane_b32 v255, s1, 46
	s_movk_i32 s0, 0xff
	v_add_u32_e32 v0, v49, v59
	v_cmp_lt_u32_e64 s[8:9], s0, v166
	v_mov_b32_e32 v51, v1
	v_mad_u32_u24 v2, v168, 12, v0
	s_movk_i32 s0, 0x1000
	v_lshlrev_b32_e32 v173, 18, v167
	v_lshlrev_b32_e32 v178, 3, v168
	v_lshl_add_u64 v[190:191], s[82:83], 0, v[50:51]
	v_add3_u32 v183, v2, v61, s0
	v_add_u32_e32 v217, 0x1000, v63
	v_add_u32_e32 v218, 0x5a00, v0
	v_add3_u32 v219, v49, v211, s0
	s_mov_b32 s41, 0
	s_mov_b32 s43, 0
	s_movk_i32 s48, 0x1280
	v_lshlrev_b32_e32 v192, 1, v4
	v_lshlrev_b32_e32 v194, 1, v48
	s_mov_b32 s42, 0x3e38aa3b
	s_brev_b32 s49, 1
	s_mov_b32 s50, 0xff800000
	v_lshlrev_b32_e32 v170, 1, v28
	v_mov_b32_e32 v220, 0x80
	v_mov_b32_e32 v221, 0x200
	v_mov_b32_e32 v222, 0x100
	v_mov_b32_e32 v223, 0x400
	v_mov_b32_e32 v224, 0x800
	v_mov_b32_e32 v225, 0x1000
	v_mov_b32_e32 v226, 0x2000
	v_mov_b32_e32 v227, 0x4000
	v_mov_b32_e32 v228, 0xffff8000
	v_mov_b32_e32 v254, 0xff800000
	s_mov_b32 s1, 0
	s_mov_b32 s51, 0
	s_barrier
	s_branch .LBB0_426

; DI u16 f2bf(float a) { return (u16)(pk_bf16(a, 0.f) & 0xffffu); }
; DI float bf2f(u16 u) { return __uint_as_float(((unsigned)u) << 16); }
; DI f32x16 zero16() { f32x16 z; for (int i = 0; i < 16; ++i) z[i] = 0.f; return z; }
; DI void dsa_attn_item(const Params& p, int b, int qblk, char* smem) {
;     ...
;   f32x16 O[2];
;   O[0] = zero16(); O[1] = zero16();
;   float mrun = -INFINITY, lrun = 0.f;
;   const unsigned thrq = thr[qtok];
;     ...
;   for (int i = tid; i < 32 * 32; i += 512) {
;     const int q = i >> 5, d = i & 31;
;     float acc = 0.f;
; #pragma unroll
;     for (int hd = 0; hd < 8; ++hd) acc = fmaf(bf2f(tm[(size_t)(b * S_ + q0 + q) * TMW + TM_WI + hd]) * 0.0625f, bf2f(qi[q * 296 + hd * 32 + d]), acc);
;     qi[q * 296 + 256 + d] = f2bf(acc);
;   }
;   __syncthreads();
;   const u16* qil = qi + lr * 296 + lh * 8;
;   const u16* kibase = (const u16*)(p.ws + OFF_KIF) + (size_t)b * 128 * 1024 + lane * 8;
;   bf16x8 Kf[4], Kn[4];
; #pragma unroll
;   for (int ks = 0; ks < 4; ++ks) Kf[ks] = ldg8(kfr + ks * 512);
;   bf16x8 Vf[2][2], Vn[2][2];
; #pragma unroll
;   for (int dt = 0; dt < 2; ++dt)
; #pragma unroll
;     for (int s = 0; s < 2; ++s) Vf[dt][s] = ldg8(vfr + (dt * 2 + s) * 512);
;   bf16x8 ki0, ki1;
;   {
;     const int kt0 = min(wave, qblk);
;     ki0 = ldg8(kibase + (size_t)kt0 * 1024); ki1 = ldg8(kibase + (size_t)kt0 * 1024 + 512);
;   }
.LBB0_432:
	v_mov_b64_e32 v[20:21], s[82:83]
	v_mad_u64_u32 v[20:21], s[10:11], v0, s48, v[20:21]
	global_load_dwordx4 v[20:23], v[20:21], off offset:2624
	ds_read_u16 v24, v18
	ds_read_u16 v25, v18 offset:64
	ds_read_u16 v26, v18 offset:128
	ds_read_u16 v27, v18 offset:192
	ds_read_u16 v28, v18 offset:256
	ds_read_u16 v29, v18 offset:320
	ds_read_u16 v30, v18 offset:384
	ds_read_u16 v31, v18 offset:448
	s_waitcnt lgkmcnt(7)
	v_lshlrev_b32_e32 v24, 16, v24
	s_waitcnt lgkmcnt(6)
	v_lshlrev_b32_e32 v25, 16, v25
	s_waitcnt lgkmcnt(5)
	v_lshlrev_b32_e32 v26, 16, v26
	s_waitcnt lgkmcnt(4)
	v_lshlrev_b32_e32 v27, 16, v27
	s_waitcnt lgkmcnt(3)
	v_lshlrev_b32_e32 v28, 16, v28
	v_add_co_u32_e32 v19, vcc, 0x200, v19
	s_waitcnt lgkmcnt(2)
	v_lshlrev_b32_e32 v29, 16, v29
	s_xor_b64 s[10:11], vcc, -1
	s_waitcnt lgkmcnt(1)
	v_lshlrev_b32_e32 v30, 16, v30
	s_and_b64 s[10:11], exec, s[10:11]
	s_waitcnt lgkmcnt(0)
	v_lshlrev_b32_e32 v31, 16, v31
	s_or_b64 s[0:1], s[10:11], s[0:1]
	v_add_u32_e32 v0, 16, v0
	s_waitcnt vmcnt(0)
	v_lshlrev_b32_e32 v32, 16, v20
	v_and_b32_e32 v20, 0xffff0000, v20
	v_mul_f32_e32 v32, 0x3d800000, v32
	v_lshlrev_b32_e32 v33, 16, v21
	v_mul_f32_e32 v20, 0x3d800000, v20
	v_fma_f32 v24, v32, v24, 0
	v_and_b32_e32 v21, 0xffff0000, v21
	v_mul_f32_e32 v33, 0x3d800000, v33
	v_fmac_f32_e32 v24, v20, v25
	v_lshlrev_b32_e32 v34, 16, v22
	v_mul_f32_e32 v21, 0x3d800000, v21
	v_fmac_f32_e32 v24, v33, v26
	v_and_b32_e32 v22, 0xffff0000, v22
	v_mul_f32_e32 v34, 0x3d800000, v34
	v_fmac_f32_e32 v24, v21, v27
	v_lshlrev_b32_e32 v35, 16, v23
	v_mul_f32_e32 v22, 0x3d800000, v22
	v_fmac_f32_e32 v24, v34, v28
	v_and_b32_e32 v23, 0xffff0000, v23
	v_mul_f32_e32 v35, 0x3d800000, v35
	v_fmac_f32_e32 v24, v22, v29
	v_mul_f32_e32 v23, 0x3d800000, v23
	v_fmac_f32_e32 v24, v35, v30
	v_fmac_f32_e32 v24, v23, v31
	v_cvt_pk_bf16_f32 v20, v24, s0
	ds_write_b16 v18, v20 offset:512
	v_add_u32_e32 v18, 0x2500, v18
	s_andn2_b64 exec, exec, s[0:1]
	s_cbranch_execnz .LBB0_432
	s_or_b64 exec, exec, s[0:1]
	s_lshl_b32 s0, s4, 21
	v_add_lshl_u32 v0, s0, v173, 1
	v_lshl_add_u64 v[198:199], v[184:185], 0, v[0:1]
	v_lshl_add_u64 v[200:201], v[186:187], 0, v[0:1]
	s_waitcnt lgkmcnt(0)
	s_barrier
	global_load_dwordx4 v[150:153], v[198:199], off
	global_load_dwordx4 v[146:149], v[198:199], off offset:1024
	global_load_dwordx4 v[142:145], v[198:199], off offset:2048
	global_load_dwordx4 v[138:141], v[198:199], off offset:3072
	global_load_dwordx4 v[126:129], v[200:201], off
	global_load_dwordx4 v[122:125], v[200:201], off offset:1024
	global_load_dwordx4 v[118:121], v[200:201], off offset:2048
	global_load_dwordx4 v[114:117], v[200:201], off offset:3072
	v_and_b32_e32 v21, 0xffff0000, v15
	v_lshlrev_b32_e32 v20, 16, v15
	v_and_b32_e32 v19, 0xffff0000, v14
	v_lshlrev_b32_e32 v18, 16, v14
	v_pk_mul_f32 v[14:15], v[20:21], s[42:43] op_sel_hi:[1,0]
	v_and_b32_e32 v21, 0xffff0000, v16
	v_lshlrev_b32_e32 v20, 16, v16
	s_lshl_b32 s40, s4, 18
	v_min_u32_e32 v0, s52, v167
	v_pk_mul_f32 v[20:21], v[20:21], s[42:43] op_sel_hi:[1,0]
	v_lshl_add_u64 v[202:203], v[180:181], 0, s[40:41]
	v_lshlrev_b32_e32 v0, 11, v0
	v_cvt_pk_bf16_f32 v100, v20, v21
	v_lshl_add_u64 v[20:21], v[202:203], 0, v[0:1]
	global_load_dwordx4 v[154:157], v[20:21], off
	global_load_dwordx4 v[158:161], v[20:21], off offset:1024
	v_and_b32_e32 v23, 0xffff0000, v17
	v_lshlrev_b32_e32 v22, 16, v17
	v_pk_mul_f32 v[18:19], v[18:19], s[42:43] op_sel_hi:[1,0]
	v_pk_mul_f32 v[16:17], v[22:23], s[42:43] op_sel_hi:[1,0]
	v_cvt_pk_bf16_f32 v98, v18, v19
	v_cvt_pk_bf16_f32 v99, v14, v15
	v_cvt_pk_bf16_f32 v101, v16, v17
	v_and_b32_e32 v15, 0xffff0000, v10
	v_lshlrev_b32_e32 v14, 16, v10
	v_and_b32_e32 v17, 0xffff0000, v11
	v_lshlrev_b32_e32 v16, 16, v11
	v_and_b32_e32 v19, 0xffff0000, v13
	v_lshlrev_b32_e32 v18, 16, v13
	v_pk_mul_f32 v[14:15], v[14:15], s[42:43] op_sel_hi:[1,0]
	v_pk_mul_f32 v[10:11], v[16:17], s[42:43] op_sel_hi:[1,0]
	v_and_b32_e32 v17, 0xffff0000, v12
	v_lshlrev_b32_e32 v16, 16, v12
	v_pk_mul_f32 v[12:13], v[18:19], s[42:43] op_sel_hi:[1,0]
	v_cvt_pk_bf16_f32 v102, v14, v15
	v_cvt_pk_bf16_f32 v105, v12, v13
	v_and_b32_e32 v13, 0xffff0000, v7
	v_lshlrev_b32_e32 v12, 16, v7
	v_and_b32_e32 v15, 0xffff0000, v9
	v_lshlrev_b32_e32 v14, 16, v9
	v_cvt_pk_bf16_f32 v103, v10, v11
	v_and_b32_e32 v11, 0xffff0000, v6
	v_lshlrev_b32_e32 v10, 16, v6
	v_pk_mul_f32 v[6:7], v[12:13], s[42:43] op_sel_hi:[1,0]
	v_and_b32_e32 v13, 0xffff0000, v8
	v_lshlrev_b32_e32 v12, 16, v8
	v_pk_mul_f32 v[8:9], v[14:15], s[42:43] op_sel_hi:[1,0]
	v_pk_mul_f32 v[10:11], v[10:11], s[42:43] op_sel_hi:[1,0]
	v_cvt_pk_bf16_f32 v109, v8, v9
	v_and_b32_e32 v9, 0xffff0000, v3
	v_lshlrev_b32_e32 v8, 16, v3
	v_cvt_pk_bf16_f32 v106, v10, v11
	v_cvt_pk_bf16_f32 v107, v6, v7
	v_and_b32_e32 v7, 0xffff0000, v2
	v_lshlrev_b32_e32 v6, 16, v2
	v_pk_mul_f32 v[2:3], v[8:9], s[42:43] op_sel_hi:[1,0]
	v_and_b32_e32 v9, 0xffff0000, v4
	v_lshlrev_b32_e32 v8, 16, v4
	v_and_b32_e32 v11, 0xffff0000, v5
	v_lshlrev_b32_e32 v10, 16, v5
	v_pk_mul_f32 v[12:13], v[12:13], s[42:43] op_sel_hi:[1,0]
	v_pk_mul_f32 v[6:7], v[6:7], s[42:43] op_sel_hi:[1,0]
	v_pk_mul_f32 v[8:9], v[8:9], s[42:43] op_sel_hi:[1,0]
	v_pk_mul_f32 v[4:5], v[10:11], s[42:43] op_sel_hi:[1,0]
	v_mov_b32_e32 v14, v1
	v_mov_b32_e32 v15, v1
	v_pk_mul_f32 v[16:17], v[16:17], s[42:43] op_sel_hi:[1,0]
	v_cvt_pk_bf16_f32 v108, v12, v13
	v_cvt_pk_bf16_f32 v110, v6, v7
	v_cvt_pk_bf16_f32 v111, v2, v3
	v_cvt_pk_bf16_f32 v112, v8, v9
	v_cvt_pk_bf16_f32 v113, v4, v5
	v_mov_b32_e32 v0, v1
	v_mov_b32_e32 v2, v1
	v_mov_b32_e32 v3, v1
	v_mov_b32_e32 v4, v1
	v_mov_b32_e32 v5, v1
	v_mov_b32_e32 v6, v1
	v_mov_b32_e32 v7, v1
	v_mov_b32_e32 v8, v1
	v_mov_b32_e32 v9, v1
	v_mov_b32_e32 v10, v1
	v_mov_b32_e32 v11, v1
	v_mov_b32_e32 v12, v1
	v_mov_b32_e32 v13, v1
	v_mov_b64_e32 v[32:33], v[14:15]
	v_cvt_pk_bf16_f32 v104, v16, v17
	v_or_b32_e32 v84, s6, v168
	v_mov_b64_e32 v[30:31], v[12:13]
	v_mov_b64_e32 v[28:29], v[10:11]
	v_mov_b64_e32 v[26:27], v[8:9]
	v_mov_b64_e32 v[24:25], v[6:7]
	v_mov_b64_e32 v[22:23], v[4:5]
	v_mov_b64_e32 v[20:21], v[2:3]
	v_mov_b64_e32 v[18:19], v[0:1]
	v_mov_b64_e32 v[16:17], v[14:15]
	s_or_b32 s4, s6, 31
	s_lshr_b32 s5, s6, 8
	v_mov_b32_e32 v83, v84
	v_mov_b32_e32 v86, v84
	v_mov_b32_e32 v85, v84
	v_mov_b32_e32 v88, v84
	v_mov_b32_e32 v87, v84
	v_mov_b32_e32 v90, v84
	v_mov_b32_e32 v89, v84
	v_mov_b32_e32 v91, v82
	v_mov_b32_e32 v92, v82
	v_mov_b32_e32 v93, v82
	v_mov_b32_e32 v94, v82
	v_mov_b32_e32 v95, v82
	v_mov_b32_e32 v96, v82
	v_mov_b32_e32 v97, v82
	s_mov_b32 s53, 0
	v_mov_b32_e32 v204, v82
	v_mov_b32_e32 v163, v82
	v_mov_b32_e32 v193, 0xff800000
	v_mov_b32_e32 v162, 0
	v_mov_b32_e32 v229, 0xff800000
	v_mov_b32_e32 v171, 0
	s_mov_b64 s[44:45], 0
	s_mov_b32 s54, 0
	v_mov_b64_e32 v[14:15], v[12:13]
	v_mov_b64_e32 v[12:13], v[10:11]
	v_mov_b64_e32 v[10:11], v[8:9]
	v_mov_b64_e32 v[8:9], v[6:7]
	v_mov_b64_e32 v[6:7], v[4:5]
	v_mov_b64_e32 v[4:5], v[2:3]
	v_mov_b64_e32 v[2:3], v[0:1]

; #define MFMA(a, b, c) __builtin_amdgcn_mfma_f32_32x32x16_bf16((a), (b), (c), 0, 0, 0)
; DI int crow(int i, int h) { return (i & 3) + 8 * (i >> 2) + 4 * h; }
; DI f32x16 zero16() { f32x16 z; for (int i = 0; i < 16; ++i) z[i] = 0.f; return z; }
; DI void dsa_attn_item(const Params& p, int b, int qblk, char* smem) {
;     ...
; #pragma unroll 2
;         for (int hd = 0; hd < 8; ++hd) {
;           f32x16 a = zero16();
;           a = MFMA(k0, *reinterpret_cast<const bf16x8*>(qil + hd * 32), a);
;           a = MFMA(k1, *reinterpret_cast<const bf16x8*>(qil + hd * 32 + 16), a);
;           const float wh = wqs[hd * 32 + lr];
; #pragma unroll
;           for (int i = 0; i < 16; ++i) sc[i] = fmaf(fabsf(a[i]), wh, sc[i]);
;         }
;         __builtin_amdgcn_sched_barrier(0);
; #pragma unroll
;         for (int i = 0; i < 16; ++i) {
;           int kp = key0 + crow(i, lh);
;           if (kp <= q0 + lr && fkey(sc[i]) >= thrq) bits |= (1u << i);
;         }
.LBB0_436:
	v_add_u32_e32 v70, s0, v219
	ds_read_b128 v[50:53], v70
	ds_read_b128 v[230:233], v70 offset:32
	ds_read_b128 v[66:69], v70 offset:64
	ds_read_b128 v[234:237], v70 offset:96
	s_addk_i32 s0, 0x80
	s_cmpk_eq_i32 s0, 0x200
	s_waitcnt lgkmcnt(3)
	v_mfma_f32_32x32x16_bf16 v[50:65], v[154:157], v[50:53], 0
	s_waitcnt lgkmcnt(1)
	v_mfma_f32_32x32x16_bf16 v[66:81], v[154:157], v[66:69], 0
	v_mfma_f32_32x32x16_bf16 v[50:65], v[158:161], v[230:233], v[50:65]
	ds_read2_b32 v[230:231], v195 offset1:32
	v_add_u32_e32 v195, 0x100, v195
	s_waitcnt lgkmcnt(0)
	v_mov_b32_e32 v232, v231
	v_mfma_f32_32x32x16_bf16 v[66:81], v[158:161], v[234:237], v[66:81]
	s_nop 6
	v_and_b32_e32 v65, 0x7fffffff, v65
	v_and_b32_e32 v64, 0x7fffffff, v64
	v_and_b32_e32 v63, 0x7fffffff, v63
	v_and_b32_e32 v62, 0x7fffffff, v62
	v_and_b32_e32 v61, 0x7fffffff, v61
	v_and_b32_e32 v60, 0x7fffffff, v60
	v_and_b32_e32 v51, 0x7fffffff, v51
	v_and_b32_e32 v50, 0x7fffffff, v50
	v_and_b32_e32 v59, 0x7fffffff, v59
	v_and_b32_e32 v58, 0x7fffffff, v58
	v_and_b32_e32 v57, 0x7fffffff, v57
	v_and_b32_e32 v56, 0x7fffffff, v56
	v_and_b32_e32 v55, 0x7fffffff, v55
	v_and_b32_e32 v54, 0x7fffffff, v54
	v_and_b32_e32 v53, 0x7fffffff, v53
	v_and_b32_e32 v52, 0x7fffffff, v52
	v_and_b32_e32 v81, 0x7fffffff, v81
	v_and_b32_e32 v80, 0x7fffffff, v80
	v_and_b32_e32 v79, 0x7fffffff, v79
	v_and_b32_e32 v78, 0x7fffffff, v78
	v_and_b32_e32 v77, 0x7fffffff, v77
	v_and_b32_e32 v76, 0x7fffffff, v76
	v_and_b32_e32 v67, 0x7fffffff, v67
	v_and_b32_e32 v66, 0x7fffffff, v66
	v_and_b32_e32 v69, 0x7fffffff, v69
	v_and_b32_e32 v68, 0x7fffffff, v68
	v_and_b32_e32 v71, 0x7fffffff, v71
	v_and_b32_e32 v70, 0x7fffffff, v70
	v_and_b32_e32 v73, 0x7fffffff, v73
	v_and_b32_e32 v72, 0x7fffffff, v72
	v_and_b32_e32 v75, 0x7fffffff, v75
	v_and_b32_e32 v74, 0x7fffffff, v74
	v_pk_fma_f32 v[34:35], v[50:51], v[230:231], v[34:35] op_sel_hi:[1,0,1]
	v_pk_fma_f32 v[36:37], v[52:53], v[230:231], v[36:37] op_sel_hi:[1,0,1]
	v_pk_fma_f32 v[38:39], v[54:55], v[230:231], v[38:39] op_sel_hi:[1,0,1]
	v_pk_fma_f32 v[40:41], v[56:57], v[230:231], v[40:41] op_sel_hi:[1,0,1]
	v_pk_fma_f32 v[42:43], v[58:59], v[230:231], v[42:43] op_sel_hi:[1,0,1]
	v_pk_fma_f32 v[44:45], v[60:61], v[230:231], v[44:45] op_sel_hi:[1,0,1]
	v_pk_fma_f32 v[46:47], v[62:63], v[230:231], v[46:47] op_sel_hi:[1,0,1]
	v_pk_fma_f32 v[48:49], v[64:65], v[230:231], v[48:49] op_sel_hi:[1,0,1]
	v_pk_fma_f32 v[34:35], v[66:67], v[232:233], v[34:35] op_sel_hi:[1,0,1]
	v_pk_fma_f32 v[42:43], v[74:75], v[232:233], v[42:43] op_sel_hi:[1,0,1]
	v_pk_fma_f32 v[40:41], v[72:73], v[232:233], v[40:41] op_sel_hi:[1,0,1]
	v_pk_fma_f32 v[38:39], v[70:71], v[232:233], v[38:39] op_sel_hi:[1,0,1]
	v_pk_fma_f32 v[36:37], v[68:69], v[232:233], v[36:37] op_sel_hi:[1,0,1]
	v_pk_fma_f32 v[44:45], v[76:77], v[232:233], v[44:45] op_sel_hi:[1,0,1]
	v_pk_fma_f32 v[46:47], v[78:79], v[232:233], v[46:47] op_sel_hi:[1,0,1]
	v_pk_fma_f32 v[48:49], v[80:81], v[232:233], v[48:49] op_sel_hi:[1,0,1]
	s_cbranch_scc0 .LBB0_436
	v_or_b32_e32 v0, v0, v214
	v_ashrrev_i32_e32 v50, 31, v34
	v_bitop3_b32 v34, v50, v34, s49 bitop3:0x36
	v_ashrrev_i32_e32 v50, 31, v35
	v_or_b32_e32 v51, 16, v0
	v_cmp_le_u32_e32 vcc, v0, v84
	v_cmp_ge_u32_e64 s[0:1], v34, v82
	v_bitop3_b32 v35, v50, v35, s49 bitop3:0x36
	v_or_b32_e32 v52, 2, v0
	v_cmp_gt_u32_e64 s[16:17], v51, v90
	v_ashrrev_i32_e32 v51, 31, v37
	s_and_b64 s[0:1], vcc, s[0:1]
	v_cmp_lt_u32_e32 vcc, v35, v82
	v_or_b32_e32 v53, 10, v0
	v_or_b32_e32 v56, 3, v0
	v_cmp_gt_u32_e64 s[14:15], v52, v84
	v_ashrrev_i32_e32 v52, 31, v43
	v_bitop3_b32 v37, v51, v37, s49 bitop3:0x36
	v_cndmask_b32_e64 v66, v254, 0, s[0:1]
	v_cndmask_b32_e64 v67, 0, v254, vcc
	v_cmp_lt_u32_e32 vcc, v0, v84
	v_or_b32_e32 v54, 9, v0
	v_or_b32_e32 v55, 17, v0
	v_or_b32_e32 v57, 11, v0
	v_cmp_gt_u32_e64 s[0:1], v56, v83
	v_cmp_gt_u32_e64 s[12:13], v53, v88
	v_ashrrev_i32_e32 v53, 31, v39
	v_bitop3_b32 v43, v52, v43, s49 bitop3:0x36
	v_cmp_lt_u32_e64 s[22:23], v37, v91
	v_cndmask_b32_e32 v67, v254, v67, vcc
	v_cmp_gt_u32_e32 vcc, v57, v87
	v_cmp_gt_u32_e64 s[6:7], v55, v89
	v_cmp_gt_u32_e64 s[10:11], v54, v85
	v_ashrrev_i32_e32 v54, 31, v40
	v_ashrrev_i32_e32 v57, 31, v38
	v_bitop3_b32 v39, v53, v39, s49 bitop3:0x36
	v_cmp_lt_u32_e64 s[24:25], v43, v97
	s_or_b64 s[0:1], s[0:1], s[22:23]
	v_ashrrev_i32_e32 v55, 31, v36
	v_bitop3_b32 v38, v57, v38, s49 bitop3:0x36
	v_bitop3_b32 v40, v54, v40, s49 bitop3:0x36
	v_cmp_lt_u32_e64 s[26:27], v39, v93
	v_cndmask_b32_e64 v69, 0, v254, s[0:1]
	s_or_b64 s[0:1], s[6:7], s[24:25]
	v_or_b32_e32 v50, 8, v0
	v_ashrrev_i32_e32 v56, 31, v42
	v_bitop3_b32 v36, v55, v36, s49 bitop3:0x36
	v_cmp_lt_u32_e64 s[28:29], v40, v94
	v_cmp_lt_u32_e64 s[36:37], v38, v92
	v_cndmask_b32_e64 v75, 0, v254, s[0:1]
	s_or_b64 s[0:1], s[10:11], s[26:27]
	v_cmp_gt_u32_e64 s[18:19], v50, v86
	v_ashrrev_i32_e32 v50, 31, v41
	v_bitop3_b32 v42, v56, v42, s49 bitop3:0x36
	v_cmp_lt_u32_e64 s[30:31], v36, v82
	v_cndmask_b32_e64 v71, 0, v254, s[0:1]
	s_or_b64 s[0:1], s[12:13], s[28:29]
	v_bitop3_b32 v41, v50, v41, s49 bitop3:0x36
	v_cmp_lt_u32_e64 s[34:35], v42, v96
	v_cndmask_b32_e64 v72, 0, v254, s[0:1]
	s_or_b64 s[0:1], s[14:15], s[30:31]
	v_cmp_lt_u32_e64 s[20:21], v41, v95
	v_cndmask_b32_e64 v68, 0, v254, s[0:1]
	s_or_b64 s[0:1], s[16:17], s[34:35]
	v_or_b32_e32 v50, 18, v0
	s_or_b64 s[20:21], vcc, s[20:21]
	v_cndmask_b32_e64 v74, 0, v254, s[0:1]
	s_or_b64 s[0:1], s[18:19], s[36:37]
	v_cmp_gt_u32_e32 vcc, v50, v84
	v_or_b32_e32 v50, 19, v0
	v_cndmask_b32_e64 v70, 0, v254, s[0:1]
	v_cmp_gt_u32_e64 s[0:1], v50, v84
	v_ashrrev_i32_e32 v50, 31, v45
	v_ashrrev_i32_e32 v51, 31, v44
; #define MFMA(a, b, c) __builtin_amdgcn_mfma_f32_32x32x16_bf16((a), (b), (c), 0, 0, 0)
; DI int crow(int i, int h) { return (i & 3) + 8 * (i >> 2) + 4 * h; }
; DI f32x16 zero16() { f32x16 z; for (int i = 0; i < 16; ++i) z[i] = 0.f; return z; }
; DI void dsa_attn_item(const Params& p, int b, int qblk, char* smem) {
;     ...
; #pragma unroll
;         for (int i = 0; i < 16; ++i) {
;           int kp = key0 + crow(i, lh);
;           if (kp <= q0 + lr && fkey(sc[i]) >= thrq) bits |= (1u << i);
;         }
;       }
;       maskbuf[(buf * 8 + wave) * 64 + lane] = (u16)bits;
;     }
;     __syncthreads();
; #pragma unroll 1
;     for (int t8 = 0; t8 < 8; ++t8) {
;       const int g = c * 8 + t8;
;       if (g > qblk) break;
;       {
;         const int gn = min(g + 1, qblk);
;         const u16* kr = kfr + (size_t)gn * 2048;
; #pragma unroll
;         for (int ks = 0; ks < 4; ++ks) Kn[ks] = ldg8(kr + ks * 512);
; #pragma unroll
;         for (int dt = 0; dt < 2; ++dt)
; #pragma unroll
;           for (int s = 0; s < 2; ++s) Vn[dt][s] = ldg8(vfr + (size_t)gn * 2048 + (dt * 2 + s) * 512);
;       }
;       const unsigned bits = maskbuf[(buf * 8 + t8) * 64 + lane];
;       f32x16 Sx = zero16();
;       __builtin_amdgcn_s_setprio(1);
; #pragma unroll
;       for (int ks = 0; ks < 4; ++ks) Sx = MFMA(Kf[ks], Qf[ks], Sx);
	v_or_b32_e32 v50, 0x80000000, v50
	v_or_b32_e32 v51, 0x80000000, v51
	v_xor_b32_e32 v45, v50, v45
	v_xor_b32_e32 v44, v51, v44
	v_cmp_lt_u32_e64 s[6:7], v45, v163
	v_cmp_lt_u32_e64 s[10:11], v44, v204
	v_or_b32_e32 v50, 24, v0
	s_or_b64 s[10:11], vcc, s[10:11]
	s_or_b64 s[0:1], s[0:1], s[6:7]
	v_cmp_gt_u32_e32 vcc, v50, v84
	v_or_b32_e32 v50, 25, v0
	v_cndmask_b32_e64 v77, 0, v254, s[0:1]
	v_cmp_gt_u32_e64 s[0:1], v50, v84
	v_ashrrev_i32_e32 v50, 31, v47
	v_ashrrev_i32_e32 v51, 31, v46
	v_or_b32_e32 v50, 0x80000000, v50
	v_or_b32_e32 v51, 0x80000000, v51
	v_xor_b32_e32 v47, v50, v47
	v_xor_b32_e32 v46, v51, v46
	v_cmp_lt_u32_e64 s[6:7], v47, v163
	v_cndmask_b32_e64 v76, 0, v254, s[10:11]
	v_cmp_lt_u32_e64 s[10:11], v46, v204
	s_or_b64 s[0:1], s[0:1], s[6:7]
	v_or_b32_e32 v50, 26, v0
	v_or_b32_e32 v0, 27, v0
	s_or_b64 s[10:11], vcc, s[10:11]
	v_cndmask_b32_e64 v79, 0, v254, s[0:1]
	v_cmp_gt_u32_e32 vcc, v50, v84
	v_cmp_gt_u32_e64 s[0:1], v0, v84
	v_ashrrev_i32_e32 v0, 31, v49
	v_ashrrev_i32_e32 v50, 31, v48
	v_or_b32_e32 v0, 0x80000000, v0
	v_or_b32_e32 v50, 0x80000000, v50
	v_xor_b32_e32 v0, v0, v49
	v_xor_b32_e32 v48, v50, v48
	v_cndmask_b32_e64 v78, 0, v254, s[10:11]
	v_cmp_lt_u32_e64 s[6:7], v0, v163
	v_cmp_lt_u32_e64 s[10:11], v48, v204
	v_cndmask_b32_e64 v73, 0, v254, s[20:21]
	s_or_b64 s[10:11], vcc, s[10:11]
	s_or_b64 s[0:1], s[0:1], s[6:7]
	v_cndmask_b32_e64 v80, 0, v254, s[10:11]
	v_cndmask_b32_e64 v81, 0, v254, s[0:1]
	s_and_b32 s0, s40, 8
	v_add_u32_e32 v50, s0, v167
	v_lshl_add_u32 v50, v50, 12, v164
	v_add_u32_e32 v50, 0x10000, v50
	ds_write_b128 v50, v[66:69]
	ds_write_b128 v50, v[70:73] offset:1024
	ds_write_b128 v50, v[74:77] offset:2048
	ds_write_b128 v50, v[78:81] offset:3072
.LBB0_438:
	s_or_b64 exec, exec, s[46:47]
	v_cndmask_b32_e64 v0, 0, 1, s[44:45]
	v_lshl_or_b32 v0, v0, 15, v164
	v_or_b32_e32 v0, 0x10000, v0
	s_mov_b32 s6, 0
	s_waitcnt lgkmcnt(0)
	s_barrier
.LBB0_439:
	ds_read_b128 v[238:241], v0
	ds_read_b128 v[242:245], v0 offset:1024
	ds_read_b128 v[246:249], v0 offset:2048
	ds_read_b128 v[250:253], v0 offset:3072
	s_add_i32 s60, s53, 1
	s_min_i32 s40, s60, s52
	s_lshl_b64 s[10:11], s[40:41], 12
	v_lshl_add_u64 v[160:161], v[198:199], 0, s[10:11]
	global_load_dwordx4 v[66:69], v[160:161], off
	global_load_dwordx4 v[70:73], v[160:161], off offset:1024
	global_load_dwordx4 v[74:77], v[160:161], off offset:2048
	global_load_dwordx4 v[78:81], v[160:161], off offset:3072
	v_lshl_add_u64 v[160:161], v[200:201], 0, s[10:11]
	global_load_dwordx4 v[50:53], v[160:161], off
	global_load_dwordx4 v[54:57], v[160:161], off offset:1024
	global_load_dwordx4 v[58:61], v[160:161], off offset:2048
	global_load_dwordx4 v[62:65], v[160:161], off offset:3072
.Lattn_hdrA:
	s_add_i32 s7, s53, s6
	s_cmp_le_u32 s7, s52
	s_cselect_b64 s[0:1], -1, 0
	s_cmp_gt_u32 s7, s52
	s_cbranch_scc1 .LBB0_446
	s_add_i32 s60, s7, 2
	s_min_i32 s40, s60, s52
	s_lshl_b64 s[10:11], s[40:41], 12
	s_waitcnt vmcnt(12) lgkmcnt(0)
	s_setprio 1
	v_mfma_f32_32x32x16_bf16 v[34:49], v[150:153], v[98:101], v[238:253]
	v_mfma_f32_32x32x16_bf16 v[34:49], v[146:149], v[102:105], v[34:49]
	v_mfma_f32_32x32x16_bf16 v[34:49], v[142:145], v[106:109], v[34:49]
	v_mfma_f32_32x32x16_bf16 v[34:49], v[138:141], v[110:113], v[34:49]
	s_setprio 0
	s_cmp_lt_u32 s6, 7
	s_cbranch_scc0 .Lattn_nokA
	v_add_u32_e32 v0, 0x1000, v0
	v_lshl_add_u64 v[160:161], v[198:199], 0, s[10:11]
	ds_read_b128 v[238:241], v0
	ds_read_b128 v[242:245], v0 offset:1024
	ds_read_b128 v[246:249], v0 offset:2048
	ds_read_b128 v[250:253], v0 offset:3072
	global_load_dwordx4 v[150:153], v[160:161], off
	global_load_dwordx4 v[146:149], v[160:161], off offset:1024
	global_load_dwordx4 v[142:145], v[160:161], off offset:2048
	global_load_dwordx4 v[138:141], v[160:161], off offset:3072
; #define MFMA(a, b, c) __builtin_amdgcn_mfma_f32_32x32x16_bf16((a), (b), (c), 0, 0, 0)
; DI void dsa_attn_item(const Params& p, int b, int qblk, char* smem) {
;     ...
;       __builtin_amdgcn_s_setprio(1);
; #pragma unroll
;       for (int ks = 0; ks < 4; ++ks) Sx = MFMA(Kf[ks], Qf[ks], Sx);
;       __builtin_amdgcn_s_setprio(0);
;       float sm[16];
; #pragma unroll
;       for (int i = 0; i < 16; ++i) {
;         const unsigned t = (unsigned)__builtin_amdgcn_sbfe((int)bits, i, 1);
;         sm[i] = __uint_as_float((t & __float_as_uint(Sx[i])) | (~t & 0xff800000u));
;       }
;       float mt = fmaxf(fmaxf(fmaxf(sm[0], sm[1]), fmaxf(sm[2], sm[3])), fmaxf(fmaxf(sm[4], sm[5]), fmaxf(sm[6], sm[7])));
;       mt = fmaxf(mt, fmaxf(fmaxf(fmaxf(sm[8], sm[9]), fmaxf(sm[10], sm[11])), fmaxf(fmaxf(sm[12], sm[13]), fmaxf(sm[14], sm[15]))));
;       mt = fmaxf(mt, __shfl_xor(mt, 32));
;       if (__builtin_amdgcn_ballot_w64(mt > mrun + 8.f) != 0ull) {
;         const float mnew = fmaxf(mrun, mt);
;         const float ms = (mnew == -INFINITY) ? 0.f : mnew;
;         const float alpha = __builtin_amdgcn_exp2f(mrun - ms);
;         lrun *= alpha;
;         mrun = mnew;
; #pragma unroll
;         for (int dt = 0; dt < 2; ++dt)
; #pragma unroll
;           for (int i = 0; i < 16; ++i) O[dt][i] *= alpha;
;       }
;       const float msafe = (mrun == -INFINITY) ? 0.f : mrun;
;       float pv[16]; float ps = 0.f;
; #pragma unroll
;       for (int i = 0; i < 16; ++i) { pv[i] = __builtin_amdgcn_exp2f(sm[i] - msafe); ps += pv[i]; }
;       lrun += ps;
;       bf16x8 Pf[2];
; #pragma unroll
;       for (int s = 0; s < 2; ++s) Pf[s] = pack8(pv[8 * s], pv[8 * s + 1], pv[8 * s + 2], pv[8 * s + 3], pv[8 * s + 4], pv[8 * s + 5], pv[8 * s + 6], pv[8 * s + 7]);
;       __builtin_amdgcn_s_setprio(1);
; #pragma unroll
;       for (int dt = 0; dt < 2; ++dt)
; #pragma unroll
;         for (int s = 0; s < 2; ++s) O[dt] = MFMA(Vf[dt][s], Pf[s], O[dt]);
;       __builtin_amdgcn_s_setprio(0);
.Lattn_nokA:
	s_nop 7
	s_nop 3
	v_max_f32_e32 v154, v36, v37
	v_max_f32_e32 v155, v40, v41
	v_max_f32_e32 v156, v42, v43
	v_max_f32_e32 v157, v44, v45
	v_max_f32_e32 v158, v48, v49
	v_max3_f32 v158, v46, v47, v158
	v_max3_f32 v154, v34, v35, v154
	v_max3_f32 v155, v38, v39, v155
	v_max3_f32 v156, v156, v157, v158
	v_max3_f32 v154, v154, v155, v156
	v_mov_b32_e32 v155, v154
	s_nop 1
	v_permlane32_swap_b32_e32 v155, v154
	v_max_f32_e32 v154, v154, v155
	v_cmp_gt_f32_e32 vcc, v154, v229
	s_cbranch_vccz .Lattn_442A
	v_max_f32_e32 v154, v154, v154
	v_max_f32_e32 v155, v193, v193
	v_max_f32_e32 v155, v155, v154
	v_cmp_neq_f32_e32 vcc, s50, v155
	v_add_f32_e32 v229, 0x41000000, v155
	s_nop 0
	v_cndmask_b32_e32 v162, 0, v155, vcc
	v_sub_f32_e32 v154, v193, v162
	v_exp_f32_e32 v154, v154
	v_mov_b32_e32 v193, v155
	v_pk_mul_f32 v[32:33], v[32:33], v[154:155] op_sel_hi:[1,0]
	v_pk_mul_f32 v[30:31], v[30:31], v[154:155] op_sel_hi:[1,0]
	v_pk_mul_f32 v[28:29], v[28:29], v[154:155] op_sel_hi:[1,0]
	v_pk_mul_f32 v[26:27], v[26:27], v[154:155] op_sel_hi:[1,0]
	v_pk_mul_f32 v[24:25], v[24:25], v[154:155] op_sel_hi:[1,0]
	v_pk_mul_f32 v[22:23], v[22:23], v[154:155] op_sel_hi:[1,0]
	v_pk_mul_f32 v[20:21], v[20:21], v[154:155] op_sel_hi:[1,0]
	v_pk_mul_f32 v[18:19], v[18:19], v[154:155] op_sel_hi:[1,0]
	v_pk_mul_f32 v[16:17], v[16:17], v[154:155] op_sel_hi:[1,0]
	v_pk_mul_f32 v[14:15], v[14:15], v[154:155] op_sel_hi:[1,0]
	v_pk_mul_f32 v[12:13], v[12:13], v[154:155] op_sel_hi:[1,0]
	v_pk_mul_f32 v[10:11], v[10:11], v[154:155] op_sel_hi:[1,0]
	v_pk_mul_f32 v[8:9], v[8:9], v[154:155] op_sel_hi:[1,0]
	v_pk_mul_f32 v[6:7], v[6:7], v[154:155] op_sel_hi:[1,0]
	v_pk_mul_f32 v[4:5], v[4:5], v[154:155] op_sel_hi:[1,0]
	v_pk_mul_f32 v[2:3], v[2:3], v[154:155] op_sel_hi:[1,0]
	v_mul_f32_e32 v171, v171, v154
.Lattn_442A:
	v_pk_add_f32 v[34:35], v[34:35], v[162:163] op_sel_hi:[1,0] neg_lo:[0,1] neg_hi:[0,1]
	v_pk_add_f32 v[36:37], v[36:37], v[162:163] op_sel_hi:[1,0] neg_lo:[0,1] neg_hi:[0,1]
	v_pk_add_f32 v[38:39], v[38:39], v[162:163] op_sel_hi:[1,0] neg_lo:[0,1] neg_hi:[0,1]
	v_pk_add_f32 v[40:41], v[40:41], v[162:163] op_sel_hi:[1,0] neg_lo:[0,1] neg_hi:[0,1]
	v_pk_add_f32 v[42:43], v[42:43], v[162:163] op_sel_hi:[1,0] neg_lo:[0,1] neg_hi:[0,1]
	v_pk_add_f32 v[44:45], v[44:45], v[162:163] op_sel_hi:[1,0] neg_lo:[0,1] neg_hi:[0,1]
	v_pk_add_f32 v[46:47], v[46:47], v[162:163] op_sel_hi:[1,0] neg_lo:[0,1] neg_hi:[0,1]
	v_pk_add_f32 v[48:49], v[48:49], v[162:163] op_sel_hi:[1,0] neg_lo:[0,1] neg_hi:[0,1]
	v_exp_f32_e32 v34, v34
	v_exp_f32_e32 v35, v35
	v_exp_f32_e32 v36, v36
	v_exp_f32_e32 v37, v37
	v_exp_f32_e32 v38, v38
	v_exp_f32_e32 v39, v39
	v_exp_f32_e32 v40, v40
	v_exp_f32_e32 v41, v41
	v_exp_f32_e32 v42, v42
	v_exp_f32_e32 v43, v43
	v_exp_f32_e32 v44, v44
	v_exp_f32_e32 v45, v45
	v_exp_f32_e32 v46, v46
	v_exp_f32_e32 v47, v47
	v_exp_f32_e32 v48, v48
	v_exp_f32_e32 v49, v49
	v_pk_add_f32 v[154:155], v[34:35], v[36:37]
	v_pk_add_f32 v[156:157], v[38:39], v[40:41]
	v_pk_add_f32 v[158:159], v[42:43], v[44:45]
	v_pk_add_f32 v[160:161], v[46:47], v[48:49]
	v_cvt_pk_bf16_f32 v34, v34, v35
	v_cvt_pk_bf16_f32 v35, v36, v37
	v_cvt_pk_bf16_f32 v36, v38, v39
	v_cvt_pk_bf16_f32 v37, v40, v41
	v_cvt_pk_bf16_f32 v38, v42, v43
	v_cvt_pk_bf16_f32 v39, v44, v45
	v_cvt_pk_bf16_f32 v40, v46, v47
	v_cvt_pk_bf16_f32 v41, v48, v49
	v_pk_add_f32 v[154:155], v[154:155], v[156:157]
	v_pk_add_f32 v[158:159], v[158:159], v[160:161]
	s_nop 0
	v_pk_add_f32 v[154:155], v[154:155], v[158:159]
	s_nop 0
	v_add_f32_e32 v154, v154, v155
	s_waitcnt vmcnt(8)
	v_add_f32_e32 v171, v171, v154
	s_setprio 1
	v_mfma_f32_32x32x16_bf16 v[18:33], v[126:129], v[34:37], v[18:33]
	v_mfma_f32_32x32x16_bf16 v[2:17], v[118:121], v[34:37], v[2:17]
	v_mfma_f32_32x32x16_bf16 v[18:33], v[122:125], v[38:41], v[18:33]
	v_mfma_f32_32x32x16_bf16 v[2:17], v[114:117], v[38:41], v[2:17]
	s_setprio 0
	s_cmp_lt_u32 s6, 7
	s_cbranch_scc0 .Lattn_novA
	v_lshl_add_u64 v[160:161], v[200:201], 0, s[10:11]
	global_load_dwordx4 v[126:129], v[160:161], off
	global_load_dwordx4 v[122:125], v[160:161], off offset:1024
	global_load_dwordx4 v[118:121], v[160:161], off offset:2048
	global_load_dwordx4 v[114:117], v[160:161], off offset:3072
.Lattn_novA:
	s_add_i32 s7, s6, 1
	s_cmp_lt_u32 s6, 7
	s_cselect_b64 s[10:11], -1, 0
	s_and_b64 s[0:1], s[0:1], s[10:11]
	s_and_b64 vcc, exec, s[0:1]
	s_cbranch_vccz .LBB0_446
	s_mov_b32 s6, s7
	s_branch .Lattn_hdrB
.Lattn_hdrB:
	s_add_i32 s7, s53, s6
	s_cmp_le_u32 s7, s52
	s_cselect_b64 s[0:1], -1, 0
	s_cmp_gt_u32 s7, s52
	s_cbranch_scc1 .LBB0_446
	s_add_i32 s60, s7, 2
	s_min_i32 s40, s60, s52
	s_lshl_b64 s[10:11], s[40:41], 12
	s_waitcnt vmcnt(12) lgkmcnt(0)
	s_setprio 1
	v_mfma_f32_32x32x16_bf16 v[34:49], v[66:69], v[98:101], v[238:253]
	v_mfma_f32_32x32x16_bf16 v[34:49], v[70:73], v[102:105], v[34:49]
	v_mfma_f32_32x32x16_bf16 v[34:49], v[74:77], v[106:109], v[34:49]
	v_mfma_f32_32x32x16_bf16 v[34:49], v[78:81], v[110:113], v[34:49]
	s_setprio 0
	s_cmp_lt_u32 s6, 7
	s_cbranch_scc0 .Lattn_nokB
	v_add_u32_e32 v0, 0x1000, v0
	v_lshl_add_u64 v[160:161], v[198:199], 0, s[10:11]
	ds_read_b128 v[238:241], v0
	ds_read_b128 v[242:245], v0 offset:1024
	ds_read_b128 v[246:249], v0 offset:2048
	ds_read_b128 v[250:253], v0 offset:3072
	global_load_dwordx4 v[66:69], v[160:161], off
	global_load_dwordx4 v[70:73], v[160:161], off offset:1024
	global_load_dwordx4 v[74:77], v[160:161], off offset:2048
	global_load_dwordx4 v[78:81], v[160:161], off offset:3072

; #define MFMA(a, b, c) __builtin_amdgcn_mfma_f32_32x32x16_bf16((a), (b), (c), 0, 0, 0)
; DI void dsa_attn_item(const Params& p, int b, int qblk, char* smem) {
;     ...
;       const float msafe = (mrun == -INFINITY) ? 0.f : mrun;
;       float pv[16]; float ps = 0.f;
; #pragma unroll
;       for (int i = 0; i < 16; ++i) { pv[i] = __builtin_amdgcn_exp2f(sm[i] - msafe); ps += pv[i]; }
;       lrun += ps;
;       bf16x8 Pf[2];
; #pragma unroll
;       for (int s = 0; s < 2; ++s) Pf[s] = pack8(pv[8 * s], pv[8 * s + 1], pv[8 * s + 2], pv[8 * s + 3], pv[8 * s + 4], pv[8 * s + 5], pv[8 * s + 6], pv[8 * s + 7]);
;       __builtin_amdgcn_s_setprio(1);
; #pragma unroll
;       for (int dt = 0; dt < 2; ++dt)
; #pragma unroll
;         for (int s = 0; s < 2; ++s) O[dt] = MFMA(Vf[dt][s], Pf[s], O[dt]);
;       __builtin_amdgcn_s_setprio(0);
.Lattn_442B:
	v_pk_add_f32 v[34:35], v[34:35], v[162:163] op_sel_hi:[1,0] neg_lo:[0,1] neg_hi:[0,1]
	v_pk_add_f32 v[36:37], v[36:37], v[162:163] op_sel_hi:[1,0] neg_lo:[0,1] neg_hi:[0,1]
	v_pk_add_f32 v[38:39], v[38:39], v[162:163] op_sel_hi:[1,0] neg_lo:[0,1] neg_hi:[0,1]
	v_pk_add_f32 v[40:41], v[40:41], v[162:163] op_sel_hi:[1,0] neg_lo:[0,1] neg_hi:[0,1]
	v_pk_add_f32 v[42:43], v[42:43], v[162:163] op_sel_hi:[1,0] neg_lo:[0,1] neg_hi:[0,1]
	v_pk_add_f32 v[44:45], v[44:45], v[162:163] op_sel_hi:[1,0] neg_lo:[0,1] neg_hi:[0,1]
	v_pk_add_f32 v[46:47], v[46:47], v[162:163] op_sel_hi:[1,0] neg_lo:[0,1] neg_hi:[0,1]
	v_pk_add_f32 v[48:49], v[48:49], v[162:163] op_sel_hi:[1,0] neg_lo:[0,1] neg_hi:[0,1]
	v_exp_f32_e32 v34, v34
	v_exp_f32_e32 v35, v35
	v_exp_f32_e32 v36, v36
	v_exp_f32_e32 v37, v37
	v_exp_f32_e32 v38, v38
	v_exp_f32_e32 v39, v39
	v_exp_f32_e32 v40, v40
	v_exp_f32_e32 v41, v41
	v_exp_f32_e32 v42, v42
	v_exp_f32_e32 v43, v43
	v_exp_f32_e32 v44, v44
	v_exp_f32_e32 v45, v45
	v_exp_f32_e32 v46, v46
	v_exp_f32_e32 v47, v47
	v_exp_f32_e32 v48, v48
	v_exp_f32_e32 v49, v49
	v_pk_add_f32 v[154:155], v[34:35], v[36:37]
	v_pk_add_f32 v[156:157], v[38:39], v[40:41]
	v_pk_add_f32 v[158:159], v[42:43], v[44:45]
	v_pk_add_f32 v[160:161], v[46:47], v[48:49]
	v_cvt_pk_bf16_f32 v34, v34, v35
	v_cvt_pk_bf16_f32 v35, v36, v37
	v_cvt_pk_bf16_f32 v36, v38, v39
	v_cvt_pk_bf16_f32 v37, v40, v41
	v_cvt_pk_bf16_f32 v38, v42, v43
	v_cvt_pk_bf16_f32 v39, v44, v45
	v_cvt_pk_bf16_f32 v40, v46, v47
	v_cvt_pk_bf16_f32 v41, v48, v49
	v_pk_add_f32 v[154:155], v[154:155], v[156:157]
	v_pk_add_f32 v[158:159], v[158:159], v[160:161]
	s_nop 0
	v_pk_add_f32 v[154:155], v[154:155], v[158:159]
	s_nop 0
	v_add_f32_e32 v154, v154, v155
	s_waitcnt vmcnt(8)
	v_add_f32_e32 v171, v171, v154
	s_setprio 1
	v_mfma_f32_32x32x16_bf16 v[18:33], v[50:53], v[34:37], v[18:33]
	v_mfma_f32_32x32x16_bf16 v[2:17], v[58:61], v[34:37], v[2:17]
	v_mfma_f32_32x32x16_bf16 v[18:33], v[54:57], v[38:41], v[18:33]
	v_mfma_f32_32x32x16_bf16 v[2:17], v[62:65], v[38:41], v[2:17]
	s_setprio 0
	s_cmp_lt_u32 s6, 7
	s_cbranch_scc0 .Lattn_novB
	v_lshl_add_u64 v[160:161], v[200:201], 0, s[10:11]
	global_load_dwordx4 v[50:53], v[160:161], off
	global_load_dwordx4 v[54:57], v[160:161], off offset:1024
	global_load_dwordx4 v[58:61], v[160:161], off offset:2048
	global_load_dwordx4 v[62:65], v[160:161], off offset:3072
